# combo8 = combo6 + at full grid barriers the non-leader workgroups poll the cross-XCD release word directly instead of waiting for their XCD leader's relay
# baseline (speedup 1.0000x reference)
; #define LAS __attribute__((address_space(3)))
; __global__ void __launch_bounds__(512, 2) mk_fwd(Args a) {
;     extern __shared__ __attribute__((aligned(16))) unsigned char lds_raw[];
;     LAS unsigned char* lds = (LAS unsigned char*)lds_raw;
;     cg::grid_group grid = cg::this_grid();
;     volatile LAS unsigned* bst = (volatile LAS unsigned*)(lds + LDS_BYTES - 16);
;     if (threadIdx.x < 2) bst[threadIdx.x] = 0u;
;     __syncthreads();
;     XcdBarrier bar; bar.bar = nullptr; bar.x = 0; bar.st = bst;
;     int redo_ = 0;
;     for (int ph = a.ph_lo; ph < a.ph_hi; ++ph) {
;         int bid_ = blockIdx.x, G_ = gridDim.x; asm volatile("" : "+s"(bid_), "+s"(G_));
;         const int G = G_, bid = bid_;
;         unsigned char* ws = a.ws; asm volatile("" : "+s"(ws));
;         const float* x_in = (const float*)a.in[0]; const float* mem = (const float*)a.in[1]; const int* positions = (const int*)a.in[2];
;         float* X = a.out;
;         unsigned* CNT = (unsigned*)(ws + WS_CNT); float* KMEAN = (float*)(ws + WS_KMEAN); float* SSQ = (float*)(ws + WS_SSQ); f32x2* ROPE = (f32x2*)(ws + WS_ROPE);
;         bf16_t* MEMB = (bf16_t*)(ws + WS_MEMB); float* MKV = (float*)(ws + WS_MKV); f32x2* ML = (f32x2*)(ws + WS_ML);
;         bf16_t* XB = (bf16_t*)(ws + WS_XB); unsigned* LIST = (unsigned*)a.out; bf16_t* VT = (bf16_t*)((unsigned char*)a.out + 32 * MiB);
;         bf16_t* H = (bf16_t*)(ws + WS_H); bf16_t* PROJ = (bf16_t*)(ws + WS_H); bf16_t* MIX = (bf16_t*)(ws + WS_MIX); bf16_t* PART = (bf16_t*)(ws + WS_PART);
;         bf16_t* WT_MKV = (bf16_t*)(ws + WS_WT);
_Z6mk_fwd4Args:
	s_mov_b64 s[70:71], s[0:1]
	s_mov_b32 s101, 0
	s_mov_b32 s98, 1
	s_mov_b32 s100, 0
	s_load_dwordx2 s[66:67], s[0:1], 0x1b0
	s_add_u32 s0, s70, 0x1b0
	s_addc_u32 s1, s71, 0
	v_and_b32_e32 v232, 0x3ff, v0
	v_writelane_b32 v254, s0, 0
	v_cmp_gt_u32_e32 vcc, 2, v232
	s_nop 0
	v_writelane_b32 v254, s1, 1
	s_and_saveexec_b64 s[0:1], vcc
	v_lshl_add_u32 v1, v232, 2, 0
	v_add_u32_e32 v1, 0x23ff0, v1
	v_mov_b32_e32 v2, 0
	ds_write_b32 v1, v2
	s_or_b64 exec, exec, s[0:1]
	s_load_dwordx2 s[72:73], s[70:71], 0x1a8
	s_waitcnt lgkmcnt(0)
	s_barrier
	s_cmp_ge_i32 s72, s73
	s_cbranch_scc1 .LBB0_729
	s_load_dwordx8 s[52:59], s[70:71], 0x80
	s_load_dwordx16 s[4:19], s[70:71], 0x0
	s_load_dwordx2 s[90:91], s[70:71], 0xa0
	s_load_dword s1, s[70:71], 0x1b8
	s_mul_i32 s0, s67, s66
	s_waitcnt lgkmcnt(0)
	s_add_u32 s96, s58, 0x2000000
	s_addc_u32 s97, s59, 0
	s_cmp_lg_u64 s[16:17], 0
	s_cselect_b64 s[20:21], -1, 0
	v_writelane_b32 v254, s20, 2
	s_cmp_lg_u64 s[52:53], 0
	v_lshrrev_b32_e32 v1, 20, v0
	v_writelane_b32 v254, s21, 3
	s_cselect_b64 s[20:21], -1, 0
	v_writelane_b32 v254, s20, 4
	s_cmp_lg_u64 s[10:11], 0
	v_lshrrev_b32_e32 v0, 10, v0
	v_writelane_b32 v254, s21, 5
	s_cselect_b64 s[20:21], -1, 0
	s_mul_i32 s67, s0, s1
	v_or_b32_e32 v0, v0, v1
	s_movk_i32 s0, 0x3ff
	v_writelane_b32 v254, s20, 6
	v_and_or_b32 v0, v0, s0, v232
	s_add_u32 s0, s90, 0x4000
	v_writelane_b32 v254, s21, 7
	s_addc_u32 s1, s91, 0
	v_writelane_b32 v254, s0, 8
	s_load_dwordx16 s[36:51], s[70:71], 0x40
	v_mbcnt_lo_u32_b32 v1, -1, 0
	v_writelane_b32 v254, s1, 9
	s_add_u32 s0, s4, 0x1c00
	v_writelane_b32 v254, s0, 10
	v_writelane_b32 v254, s4, 11
	s_addc_u32 s0, s5, 0
	v_mov_b32_e32 v129, 0
	v_writelane_b32 v254, s5, 12
	v_writelane_b32 v254, s6, 13
	v_writelane_b32 v254, s7, 14
	v_writelane_b32 v254, s8, 15
	v_writelane_b32 v254, s9, 16
	v_writelane_b32 v254, s10, 17
	v_writelane_b32 v254, s11, 18
	v_writelane_b32 v254, s12, 19
	v_writelane_b32 v254, s13, 20
	v_writelane_b32 v254, s14, 21
	v_writelane_b32 v254, s15, 22
	v_writelane_b32 v254, s16, 23
	v_writelane_b32 v254, s17, 24
	v_writelane_b32 v254, s18, 25
	v_writelane_b32 v254, s19, 26
	v_writelane_b32 v254, s0, 27
	s_add_i32 s0, 0, 0x11000
	v_writelane_b32 v254, s0, 28
	s_add_i32 s0, 0, 0x22804
	v_writelane_b32 v254, s0, 29
	s_add_i32 s0, 0, 0x22808
	v_writelane_b32 v254, s0, 30
	s_add_i32 s0, 0, 0x2280c
	v_writelane_b32 v254, s0, 31
	s_add_i32 s0, 0, 0x22810
	v_writelane_b32 v254, s0, 32
	s_add_i32 s0, 0, 0x22814
	v_writelane_b32 v254, s0, 33
	s_add_i32 s0, 0, 0x22818
	v_writelane_b32 v254, s0, 34
	s_add_i32 s0, 0, 0x2281c
	v_writelane_b32 v254, s0, 35
	s_add_i32 s0, 0, 0x227fc
	v_writelane_b32 v254, s0, 36
	s_add_i32 s0, 0, 0x23ff0
	v_writelane_b32 v254, s0, 37
	s_add_i32 s0, 0, 0x23ff4
	v_writelane_b32 v254, s0, 38
	s_mov_b32 s0, 0
	v_writelane_b32 v254, s0, 39
	v_cmp_eq_u32_e64 s[0:1], 0, v232
	s_mov_b32 s14, s72
	s_movk_i32 s86, 0x110
	v_writelane_b32 v254, s0, 40
	s_mov_b32 s69, 0xf149f2ca
	s_mov_b32 s87, 0x3e0293ee
	v_writelane_b32 v254, s1, 41
	v_cmp_eq_u32_e64 s[0:1], 0, v0
	v_mov_b32_e32 v233, 1
	v_mov_b32_e32 v234, 0x358637bd
	v_writelane_b32 v254, s0, 42
	s_mov_b32 s33, 0xf800000
	v_mov_b32_e32 v235, 0x260
	v_writelane_b32 v254, s1, 43
	v_writelane_b32 v254, s2, 44
	v_writelane_b32 v254, s70, 45
	s_movk_i32 s62, 0x1000
	s_mov_b32 s63, 0xb000
	v_writelane_b32 v254, s71, 46
	v_writelane_b32 v254, s90, 47
	v_mov_b32_e32 v236, 0x2000
	v_mbcnt_hi_u32_b32 v237, -1, v1
	v_writelane_b32 v254, s91, 48
	v_writelane_b32 v254, s96, 49
	v_mov_b32_e32 v238, 0xff800000
	v_mov_b32_e32 v239, 0xffffea00
	v_writelane_b32 v254, s97, 50
	v_writelane_b32 v254, s66, 51
	v_mov_b32_e32 v240, 0x80
	v_mov_b32_e32 v241, 0x5f
	v_writelane_b32 v254, s67, 52
	v_writelane_b32 v254, s72, 53
	v_mov_b32_e32 v242, 0x67
	v_mov_b32_e32 v243, 0x6f
	v_writelane_b32 v254, s73, 54
	v_mov_b32_e32 v244, 0x77
	v_mov_b32_e32 v245, 0x7f
	s_movk_i32 s3, 0x2c00
	s_mov_b64 s[78:79], 0
	s_mov_b32 s75, 0
	s_mov_b64 s[76:77], 0x80
	v_writelane_b32 v254, s67, 55
	s_branch .LBB0_8

; __device__ __forceinline__ unsigned xb_ld(unsigned* p)              { return __hip_atomic_load(p, __ATOMIC_RELAXED, __HIP_MEMORY_SCOPE_AGENT); }
; __device__ __forceinline__ unsigned xb_add(unsigned* p, unsigned v) { return __hip_atomic_fetch_add(p, v, __ATOMIC_RELAXED, __HIP_MEMORY_SCOPE_AGENT); }
; #define XB_SPIN(cond, bar) do { unsigned _sp = 0; while (cond) { __builtin_amdgcn_s_sleep(1); \
;     if ((++_sp & 255u) == 0u) { if (xb_ld(&(bar)[XB_TMO])) break; if (_sp > XB_SPIN_CAP) { atomicAdd(&(bar)[XB_TMO], 1u); break; } } } } while (0)
; __device__ __forceinline__ void xcd_barrier(const XcdBarrier& b) {
;     ...
;         const unsigned old = xb_add(&bar[XB_XSUB(b.x)], 1u);
;         const unsigned gen = old / nloc;
;         if (old + 1u == (gen + 1u) * nloc) {
;             __builtin_amdgcn_fence(__ATOMIC_RELEASE, "agent");
;             asm volatile("s_waitcnt vmcnt(0)" ::: "memory");
;             const unsigned og = xb_add(&bar[XB_TOP], 1u);
;             const unsigned tg = og / nx;
;             if (og + 1u == (tg + 1u) * nx) xb_add(&bar[XB_TOPGEN], 1u);
;             else XB_SPIN(xb_ld(&bar[XB_TOPGEN]) == tg, bar);
;             __builtin_amdgcn_fence(__ATOMIC_ACQUIRE, "agent");
;             xb_add(&bar[XB_XGEN(b.x)], 1u);
;             asm volatile("s_waitcnt vmcnt(0)" ::: "memory");
;         } else {
;             XB_SPIN(xb_ld(&bar[XB_XGEN(b.x)]) == gen, bar);
.LBB0_685:
	v_readlane_b32 s4, v254, 39
	s_lshl_b32 s74, s4, 6
	s_lshl_b64 s[4:5], s[74:75], 2
	s_add_u32 s4, s78, s4
	s_addc_u32 s5, s79, s5
	v_mov_b32_e32 v1, 0x1000
	global_atomic_add v3, v1, v233, s[4:5] offset:1024 sc0
	v_cvt_f32_u32_e32 v1, v2
	v_sub_u32_e32 v4, 0, v2
	v_rcp_iflag_f32_e32 v1, v1
	s_nop 0
	v_mul_f32_e32 v1, 0x4f7ffffe, v1
	v_cvt_u32_f32_e32 v1, v1
	v_mul_lo_u32 v4, v4, v1
	v_mul_hi_u32 v4, v1, v4
	v_add_u32_e32 v1, v1, v4
	s_waitcnt vmcnt(0)
	v_mul_hi_u32 v1, v3, v1
	v_mul_lo_u32 v4, v1, v2
	v_sub_u32_e32 v4, v3, v4
	v_add_u32_e32 v5, 1, v1
	v_cmp_ge_u32_e32 vcc, v4, v2
	v_add_u32_e32 v3, 1, v3
	s_nop 0
	v_cndmask_b32_e32 v1, v1, v5, vcc
	v_sub_u32_e32 v5, v4, v2
	v_cndmask_b32_e32 v4, v4, v5, vcc
	v_add_u32_e32 v5, 1, v1
	v_cmp_ge_u32_e32 vcc, v4, v2
	s_nop 1
	v_cndmask_b32_e32 v1, v1, v5, vcc
	v_mul_lo_u32 v4, v2, v1
	v_add_u32_e32 v2, v4, v2
	v_cmp_ne_u32_e32 vcc, v3, v2
	s_and_saveexec_b64 s[6:7], vcc
	s_xor_b64 s[6:7], exec, s[6:7]
	s_cbranch_execz .LBB0_698
	s_waitcnt lgkmcnt(0)
	s_add_u32 s10, s4, 0x2400
	s_addc_u32 s11, s5, 0
	s_cmp_lg_u32 s98, 0
	s_cbranch_scc1 .Lnl_full
	s_mov_b32 s99, 0x181e04
	s_bitcmp1_b32 s99, s100
	s_cbranch_scc1 .Lnl_go
.Lnl_full:
	s_add_u32 s10, s78, 0x3500
	s_addc_u32 s11, s79, 0
	v_mov_b32_e32 v1, s101
.Lnl_go:
	global_load_dword v0, v129, s[10:11] sc1
	s_waitcnt vmcnt(0)
	v_cmp_le_u32_e32 vcc, v0, v1
	s_and_saveexec_b64 s[8:9], vcc
	s_cbranch_execz .LBB0_697
	s_mov_b32 s15, 1
	s_mov_b64 s[12:13], 0
	s_branch .LBB0_689

; __device__ __forceinline__ unsigned xb_ld(unsigned* p)              { return __hip_atomic_load(p, __ATOMIC_RELAXED, __HIP_MEMORY_SCOPE_AGENT); }
; #define XB_SPIN(cond, bar) do { unsigned _sp = 0; while (cond) { __builtin_amdgcn_s_sleep(1); \
;     if ((++_sp & 255u) == 0u) { if (xb_ld(&(bar)[XB_TMO])) break; if (_sp > XB_SPIN_CAP) { atomicAdd(&(bar)[XB_TMO], 1u); break; } } } } while (0)
; __device__ __forceinline__ void xcd_barrier(const XcdBarrier& b) {
;     ...
;             XB_SPIN(xb_ld(&bar[XB_XGEN(b.x)]) == gen, bar);
.LBB0_691:
	global_load_dword v0, v129, s[10:11] sc1
	s_add_i32 s15, s15, 1
	s_mov_b64 s[34:35], -1
	s_waitcnt vmcnt(0)
	v_cmp_gt_u32_e32 vcc, v0, v1
	s_orn2_b64 s[30:31], vcc, exec
	s_branch .LBB0_688

; __device__ __forceinline__ void xcd_barrier(const XcdBarrier& b) {
;     ...
;         }
;     }
;     __syncthreads();
.LBB0_714:
	s_or_b64 exec, exec, s[0:1]
	s_cmp_lg_u32 s98, 0
	s_cbranch_scc1 .Lcnt_full
	s_mov_b32 s99, 0x181e04
	s_bitcmp1_b32 s99, s100
	s_cbranch_scc1 .Lcnt_skip
.Lcnt_full:
	s_add_i32 s101, s101, 1
.Lcnt_skip:
	s_mov_b64 s[0:1], 0
	s_waitcnt lgkmcnt(0)
	s_barrier

; __global__ void __launch_bounds__(512, 2) mk_fwd(Args a) {
	.amdhsa_kernel _Z6mk_fwd4Args
		.amdhsa_group_segment_fixed_size 0
		.amdhsa_private_segment_fixed_size 0
		.amdhsa_kernarg_size 688
		.amdhsa_user_sgpr_count 2
		.amdhsa_user_sgpr_dispatch_ptr 0
		.amdhsa_user_sgpr_queue_ptr 0
		.amdhsa_user_sgpr_kernarg_segment_ptr 1
		.amdhsa_user_sgpr_dispatch_id 0
		.amdhsa_user_sgpr_kernarg_preload_length 0
		.amdhsa_user_sgpr_kernarg_preload_offset 0
		.amdhsa_user_sgpr_private_segment_size 0
		.amdhsa_uses_dynamic_stack 0
		.amdhsa_enable_private_segment 0
		.amdhsa_system_sgpr_workgroup_id_x 1
		.amdhsa_system_sgpr_workgroup_id_y 0
		.amdhsa_system_sgpr_workgroup_id_z 0
		.amdhsa_system_sgpr_workgroup_info 0
		.amdhsa_system_vgpr_workitem_id 2
		.amdhsa_next_free_vgpr 256
		.amdhsa_next_free_sgpr 102
		.amdhsa_accum_offset 256
		.amdhsa_reserve_vcc 1
		.amdhsa_float_round_mode_32 0
		.amdhsa_float_round_mode_16_64 0
		.amdhsa_float_denorm_mode_32 3
		.amdhsa_float_denorm_mode_16_64 3
		.amdhsa_dx10_clamp 1
		.amdhsa_ieee_mode 1
		.amdhsa_fp16_overflow 0
		.amdhsa_tg_split 0
		.amdhsa_exception_fp_ieee_invalid_op 0
		.amdhsa_exception_fp_denorm_src 0
		.amdhsa_exception_fp_ieee_div_zero 0
		.amdhsa_exception_fp_ieee_overflow 0
		.amdhsa_exception_fp_ieee_underflow 0
		.amdhsa_exception_fp_ieee_inexact 0
		.amdhsa_exception_int_div_zero 0
	.end_amdhsa_kernel

; __global__ void __launch_bounds__(512, 2) mk_fwd(Args a) {
amdhsa.kernels:
  - .agpr_count:     0
    .args:
      - .offset:         0
        .size:           432
        .value_kind:     by_value
      - .offset:         432
        .size:           4
        .value_kind:     hidden_block_count_x
      - .offset:         436
        .size:           4
        .value_kind:     hidden_block_count_y
      - .offset:         440
        .size:           4
        .value_kind:     hidden_block_count_z
      - .offset:         444
        .size:           2
        .value_kind:     hidden_group_size_x
      - .offset:         446
        .size:           2
        .value_kind:     hidden_group_size_y
      - .offset:         448
        .size:           2
        .value_kind:     hidden_group_size_z
      - .offset:         450
        .size:           2
        .value_kind:     hidden_remainder_x
      - .offset:         452
        .size:           2
        .value_kind:     hidden_remainder_y
      - .offset:         454
        .size:           2
        .value_kind:     hidden_remainder_z
      - .offset:         472
        .size:           8
        .value_kind:     hidden_global_offset_x
      - .offset:         480
        .size:           8
        .value_kind:     hidden_global_offset_y
      - .offset:         488
        .size:           8
        .value_kind:     hidden_global_offset_z
      - .offset:         496
        .size:           2
        .value_kind:     hidden_grid_dims
      - .offset:         520
        .size:           8
        .value_kind:     hidden_multigrid_sync_arg
      - .offset:         552
        .size:           4
        .value_kind:     hidden_dynamic_lds_size
    .group_segment_fixed_size: 0
    .kernarg_segment_align: 8
    .kernarg_segment_size: 688
    .language:       OpenCL C
    .language_version:
      - 2
      - 0
    .max_flat_workgroup_size: 512
    .name:           _Z6mk_fwd4Args
    .private_segment_fixed_size: 0
    .sgpr_count:     108
    .sgpr_spill_count: 90
    .symbol:         _Z6mk_fwd4Args.kd
    .uniform_work_group_size: 1
    .uses_dynamic_stack: false
    .vgpr_count:     256
    .vgpr_spill_count: 0
    .wavefront_size: 64
